# HGRN phase A: batch the prefix-sum stage LDS reads (on top of phase C changes)
# baseline (speedup 1.0000x reference)
.LBB0_573:
	v_lshlrev_b32_e32 v96, 16, v84
	v_and_b32_e32 v97, 0xffff0000, v84
	v_lshlrev_b32_e32 v98, 16, v85
	v_and_b32_e32 v99, 0xffff0000, v85
	v_lshlrev_b32_e32 v88, 16, v86
	v_and_b32_e32 v89, 0xffff0000, v86
	v_lshlrev_b32_e32 v90, 16, v87
	v_and_b32_e32 v91, 0xffff0000, v87
	v_lshlrev_b32_e32 v92, 16, v80
	v_and_b32_e32 v93, 0xffff0000, v80
	v_lshlrev_b32_e32 v94, 16, v81
	v_and_b32_e32 v95, 0xffff0000, v81
	v_lshlrev_b32_e32 v84, 16, v82
	v_and_b32_e32 v85, 0xffff0000, v82
	v_lshlrev_b32_e32 v86, 16, v83
	v_and_b32_e32 v87, 0xffff0000, v83
	ds_write_b128 v123, v[96:99]
	ds_write_b128 v123, v[88:91] offset:16
	ds_write_b128 v123, v[92:95] offset:16384
	ds_write_b128 v123, v[84:87] offset:16400
	ds_write_b16 v124, v76
	ds_write_b16_d16_hi v124, v76 offset:80
	ds_write_b16 v124, v77 offset:160
	ds_write_b16_d16_hi v124, v77 offset:240
	ds_write_b16 v124, v78 offset:320
	ds_write_b16_d16_hi v124, v78 offset:400
	ds_write_b16 v124, v79 offset:480
	ds_write_b16_d16_hi v124, v79 offset:560
	s_waitcnt lgkmcnt(0)
	s_barrier
	v_mov_b32_e32 v76, 0
	s_and_saveexec_b64 s[12:13], s[6:7]
	s_cbranch_execz .LBB0_577
	v_mov_b32_e32 v76, 0
	ds_read_b32 v226, v127
	ds_read_b32 v227, v127 offset:512
	ds_read_b32 v228, v127 offset:1024
	ds_read_b32 v229, v127 offset:1536
	ds_read_b32 v230, v127 offset:2048
	ds_read_b32 v231, v127 offset:2560
	ds_read_b32 v232, v127 offset:3072
	ds_read_b32 v233, v127 offset:3584
	ds_read_b32 v234, v127 offset:4096
	ds_read_b32 v235, v127 offset:4608
	ds_read_b32 v236, v127 offset:5120
	ds_read_b32 v237, v127 offset:5632
	ds_read_b32 v238, v127 offset:6144
	ds_read_b32 v239, v127 offset:6656
	ds_read_b32 v240, v127 offset:7168
	ds_read_b32 v241, v127 offset:7680
	s_waitcnt lgkmcnt(0)
	v_add_f32_e32 v76, v76, v226
	v_add_f32_e32 v76, v76, v227
	v_add_f32_e32 v76, v76, v228
	v_add_f32_e32 v76, v76, v229
	v_add_f32_e32 v76, v76, v230
	v_add_f32_e32 v76, v76, v231
	v_add_f32_e32 v76, v76, v232
	v_add_f32_e32 v76, v76, v233
	v_add_f32_e32 v76, v76, v234
	v_add_f32_e32 v76, v76, v235
	v_add_f32_e32 v76, v76, v236
	v_add_f32_e32 v76, v76, v237
	v_add_f32_e32 v76, v76, v238
	v_add_f32_e32 v76, v76, v239
	v_add_f32_e32 v76, v76, v240
	v_add_f32_e32 v76, v76, v241
.LBB0_577:
	s_or_b64 exec, exec, s[12:13]
	ds_read_b32 v226, v134
	ds_read_b32 v227, v134 offset:512
	ds_read_b32 v228, v134 offset:1024
	ds_read_b32 v229, v134 offset:1536
	ds_read_b32 v230, v134 offset:2048
	ds_read_b32 v231, v134 offset:2560
	ds_read_b32 v232, v134 offset:3072
	ds_read_b32 v233, v136
	ds_read_b32 v234, v134 offset:4096
	ds_read_b32 v235, v134 offset:4608
	ds_read_b32 v236, v134 offset:5120
	ds_read_b32 v237, v134 offset:5632
	ds_read_b32 v238, v134 offset:6144
	ds_read_b32 v239, v134 offset:6656
	ds_read_b32 v240, v134 offset:7168
	ds_read_b32 v241, v138
	s_waitcnt lgkmcnt(0)
	v_add_f32_e32 v242, v76, v226
	ds_write_b32 v135, v242
	v_add_f32_e32 v76, v242, v227
	ds_write_b32 v135, v76 offset:512
	v_add_f32_e32 v242, v76, v228
	ds_write_b32 v135, v242 offset:1024
	v_add_f32_e32 v76, v242, v229
	ds_write_b32 v135, v76 offset:1536
	v_add_f32_e32 v242, v76, v230
	ds_write_b32 v135, v242 offset:2048
	v_add_f32_e32 v76, v242, v231
	ds_write_b32 v135, v76 offset:2560
	v_add_f32_e32 v242, v76, v232
	ds_write_b32 v135, v242 offset:3072
	v_add_f32_e32 v76, v242, v233
	ds_write_b32 v137, v76
	v_add_f32_e32 v242, v76, v234
	ds_write_b32 v135, v242 offset:4096
	v_add_f32_e32 v76, v242, v235
	ds_write_b32 v135, v76 offset:4608
	v_add_f32_e32 v242, v76, v236
	ds_write_b32 v135, v242 offset:5120
	v_add_f32_e32 v76, v242, v237
	ds_write_b32 v135, v76 offset:5632
	v_add_f32_e32 v242, v76, v238
	ds_write_b32 v135, v242 offset:6144
	v_add_f32_e32 v76, v242, v239
	ds_write_b32 v135, v76 offset:6656
	v_add_f32_e32 v242, v76, v240
	ds_write_b32 v135, v242 offset:7168
	v_add_f32_e32 v76, v242, v241
	ds_write_b32 v139, v76
	s_and_saveexec_b64 s[12:13], s[0:1]
	s_cbranch_execz .LBB0_579
	v_mul_f32_e32 v76, 0x3fb8aa3b, v76
	v_exp_f32_e32 v76, v76
	ds_write_b32 v128, v76
